# attention: Q fragments kept in registers for the whole pass (diff: all 4, MoBA: 7 of 8) instead of per-tile serialized LDS reads; plus post-phase de-serialization
# speedup vs baseline: 1.0048x; 1.0048x over previous
; #define LAS __attribute__((address_space(3)))
; template <int DQ, bool QLDS, int KD  >
; __device__ __forceinline__ void attn_pass(const bf16_t* qrow  , const bf16_t* kbase  , const bf16_t* vbase  ,
;                                           int qt, int own, unsigned selmask, int r, int h, f32x16 (&O)[4], LAS unsigned char* wlds  ) {
;     ...
;     if constexpr (QLDS) {
; #pragma unroll
;         for (int ks = 0; ks < NKS; ++ks) *(LAS bf16x8*)(wlds + ks * 1024) = *(const bf16x8*)(qrow + 16 * ks);
;     } else {
; #pragma unroll
;         for (int ks = 0; ks < NKS; ++ks) qf[ks] = *(const bf16x8*)(qrow + 16 * ks);
;     }
.LBB0_153:
	global_load_dwordx4 v[216:219], v[24:25], off
	global_load_dwordx4 v[230:233], v[24:25], off offset:32
	global_load_dwordx4 v[234:237], v[24:25], off offset:64
	global_load_dwordx4 v[238:241], v[24:25], off offset:96
	global_load_dwordx4 v[242:245], v[24:25], off offset:128
	global_load_dwordx4 v[246:249], v[24:25], off offset:160
	global_load_dwordx4 v[250:253], v[24:25], off offset:192
	global_load_dwordx4 v[2:5], v[24:25], off offset:224
	v_lshl_add_u32 v201, v200, 4, s52
	s_lshl_b32 s5, s21, 7
	s_lshr_b32 s2, s92, 3
	s_mov_b32 s8, 0
	s_cmp_lt_u32 s92, 8
	s_waitcnt vmcnt(0)
	ds_write_b128 v201, v[2:5] offset:7168
	s_cbranch_scc1 .LBB0_156
	s_mov_b32 s9, 0

.LBB0_159:
	v_mov_b32_e32 v0, v201
	ds_read_b128 v[2:5], v0 offset:7168
	s_waitcnt vmcnt(8)
	s_cmp_lg_u32 s86, s92
	v_mfma_f32_32x32x16_bf16 v[80:95], v[100:103], v[216:219], 0
	v_mfma_f32_32x32x16_bf16 v[80:95], v[140:143], v[230:233], v[80:95]
	v_mfma_f32_32x32x16_bf16 v[80:95], v[144:147], v[234:237], v[80:95]
	v_mfma_f32_32x32x16_bf16 v[80:95], v[148:151], v[238:241], v[80:95]
	v_mfma_f32_32x32x16_bf16 v[80:95], v[152:155], v[242:245], v[80:95]
	v_mfma_f32_32x32x16_bf16 v[80:95], v[156:159], v[246:249], v[80:95]
	v_mfma_f32_32x32x16_bf16 v[80:95], v[160:163], v[250:253], v[80:95]
	s_waitcnt lgkmcnt(0)
	v_mfma_f32_32x32x16_bf16 v[80:95], v[164:167], v[2:5], v[80:95]
	s_cbranch_scc1 .LBB0_161
	s_nop 10
	v_cndmask_b32_e64 v0, v80, v226, s[8:9]
	v_cndmask_b32_e64 v81, v226, v81, s[10:11]
	v_cndmask_b32_e64 v80, v0, v80, s[10:11]
	v_cndmask_b32_e64 v82, v82, v226, s[12:13]
	v_cndmask_b32_e64 v83, v83, v226, s[14:15]
	v_cndmask_b32_e64 v84, v84, v226, s[16:17]
	v_cndmask_b32_e64 v85, v85, v226, s[18:19]
	v_cndmask_b32_e64 v86, v86, v226, s[20:21]
	v_cndmask_b32_e64 v87, v87, v226, s[22:23]
	v_cndmask_b32_e64 v88, v88, v226, s[24:25]
	v_cndmask_b32_e64 v89, v89, v226, s[26:27]
	v_cndmask_b32_e64 v90, v90, v226, s[28:29]
	v_cndmask_b32_e64 v91, v91, v226, s[30:31]
	v_cndmask_b32_e64 v92, v92, v226, s[34:35]
	v_cndmask_b32_e64 v93, v93, v226, s[36:37]
	v_cndmask_b32_e64 v94, v94, v226, s[38:39]
	v_cndmask_b32_e64 v95, v95, v226, s[40:41]

; #define ATTN_NEXT(k) (((((k) + 1) & 7) == 0) ? ((k) + 1 + 8 * __builtin_ctz(bmask >> (((k) + 1) >> 3))) : ((k) + 1))
; template <int DQ, bool QLDS, int KD  >
; __device__ __forceinline__ void attn_pass(const bf16_t* qrow  , const bf16_t* kbase  , const bf16_t* vbase  ,
;                                           int qt, int own, unsigned selmask, int r, int h, f32x16 (&O)[4], LAS unsigned char* wlds  ) {
;     ...
;     int k1 = ATTN_NEXT(kt);
;     asm volatile("s_waitcnt vmcnt(0)" ::: "memory");
;     if constexpr (KD == 2) {
;         issue_k<NKS>(kfa, kbase + (size_t)kt * (NKS * 512));            issue_v(vfa, vbase + (size_t)kt * 4096);
;         issue_k<NKS>(kfb, kbase + (size_t)ATTN_CLAMP(k1) * (NKS * 512)); issue_v(vfb, vbase + (size_t)ATTN_CLAMP(k1) * 4096);
;     } else {
;         issue_v(vfa, vbase + (size_t)kt * 4096); issue_k<NKS>(kfa, kbase + (size_t)kt * (NKS * 512)); issue_v(vfb, vbase + (size_t)ATTN_CLAMP(k1) * 4096);
;     }
.LBB0_163:
	s_add_i32 s42, s87, 1
	s_ashr_i32 s54, s42, 3
	s_lshr_b32 s54, s59, s54
	s_ff1_i32_b32 s54, s54
	s_and_b32 s43, s42, 7
	s_lshl_b32 s54, s54, 3
	s_cmp_eq_u32 s43, 0
	s_cselect_b32 s43, s54, 0
	s_add_i32 s86, s43, s42
	s_min_i32 s42, s87, s92
	s_ashr_i32 s43, s42, 31
	s_lshl_b64 s[42:43], s[42:43], 13
	v_lshl_add_u64 v[82:83], v[206:207], 0, s[42:43]
	global_load_dwordx4 v[100:103], v[82:83], off offset:0
	global_load_dwordx4 v[140:143], v[82:83], off offset:0x400
	global_load_dwordx4 v[144:147], v[82:83], off offset:0x800
	v_sub_f32_e32 v11, v11, v203
	v_sub_f32_e32 v14, v14, v203
	v_sub_f32_e32 v15, v15, v203
	v_sub_f32_e32 v80, v80, v203
	v_sub_f32_e32 v13, v13, v203
	v_sub_f32_e32 v12, v12, v203
	v_sub_f32_e32 v10, v10, v203
	v_sub_f32_e32 v9, v9, v203
	global_load_dwordx4 v[148:151], v[82:83], off offset:0xc00
	v_exp_f32_e32 v11, v11
	v_exp_f32_e32 v14, v14
	v_exp_f32_e32 v15, v15
	v_exp_f32_e32 v210, v80
	v_exp_f32_e32 v13, v13
	v_exp_f32_e32 v12, v12
	v_exp_f32_e32 v10, v10
	v_exp_f32_e32 v9, v9
	v_lshl_add_u64 v[82:83], v[82:83], 0, s[78:79]
	global_load_dwordx4 v[152:155], v[82:83], off offset:0
	global_load_dwordx4 v[156:159], v[82:83], off offset:0x400
	global_load_dwordx4 v[160:163], v[82:83], off offset:0x800
	global_load_dwordx4 v[164:167], v[82:83], off offset:0xc00
	v_cvt_pk_bf16_f32 v80, v11, v14
	v_cvt_pk_bf16_f32 v81, v15, v210
	v_cvt_pk_bf16_f32 v82, v13, v12
	v_cvt_pk_bf16_f32 v83, v10, v9
	s_waitcnt vmcnt(16)
	v_sub_f32_e32 v8, v8, v203
	v_sub_f32_e32 v7, v7, v203
	v_mfma_f32_32x32x16_bf16 v[64:79], v[96:99], v[80:83], v[64:79]
	v_sub_f32_e32 v6, v6, v203
	v_sub_f32_e32 v5, v5, v203
	v_sub_f32_e32 v4, v4, v203
	v_sub_f32_e32 v3, v3, v203
	v_sub_f32_e32 v2, v2, v203
	v_sub_f32_e32 v0, v0, v203
	v_exp_f32_e32 v8, v8
	v_mfma_f32_32x32x16_bf16 v[48:63], v[116:119], v[80:83], v[48:63]
	v_exp_f32_e32 v7, v7
	v_exp_f32_e32 v6, v6
	v_exp_f32_e32 v5, v5
	v_exp_f32_e32 v4, v4
	v_exp_f32_e32 v3, v3
	v_exp_f32_e32 v2, v2
	v_exp_f32_e32 v0, v0
	v_mfma_f32_32x32x16_bf16 v[32:47], v[124:127], v[80:83], v[32:47]
	s_min_i32 s56, s86, s92
	v_cvt_pk_bf16_f32 v84, v8, v7
	v_cvt_pk_bf16_f32 v85, v6, v5
	v_cvt_pk_bf16_f32 v86, v4, v3
	v_cvt_pk_bf16_f32 v87, v2, v0
	s_ashr_i32 s57, s56, 31
	s_lshl_b64 s[42:43], s[56:57], 13
	v_mfma_f32_32x32x16_bf16 v[16:31], v[132:135], v[80:83], v[16:31]
	v_lshl_add_u64 v[80:81], v[208:209], 0, s[42:43]
	v_lshl_add_u64 v[82:83], v[80:81], 0, s[78:79]
	v_mov_b32_e32 v211, v201
	s_cmp_lg_u32 s87, s92
	v_mfma_f32_32x32x16_bf16 v[64:79], v[112:115], v[84:87], v[64:79]
	v_mfma_f32_32x32x16_bf16 v[48:63], v[120:123], v[84:87], v[48:63]
	v_mfma_f32_32x32x16_bf16 v[32:47], v[128:131], v[84:87], v[32:47]
	v_mfma_f32_32x32x16_bf16 v[16:31], v[136:139], v[84:87], v[16:31]
	global_load_dwordx4 v[96:99], v[80:81], off offset:0
	global_load_dwordx4 v[112:115], v[80:81], off offset:0x400
	global_load_dwordx4 v[116:119], v[80:81], off offset:0x800
	global_load_dwordx4 v[120:123], v[80:81], off offset:0xc00
	global_load_dwordx4 v[124:127], v[82:83], off offset:0
	global_load_dwordx4 v[128:131], v[82:83], off offset:0x400
	global_load_dwordx4 v[132:135], v[82:83], off offset:0x800
	global_load_dwordx4 v[136:139], v[82:83], off offset:0xc00
	ds_read_b128 v[212:215], v211 offset:7168
	s_waitcnt vmcnt(8)
	v_mfma_f32_32x32x16_bf16 v[80:95], v[100:103], v[216:219], 0
	v_mfma_f32_32x32x16_bf16 v[80:95], v[140:143], v[230:233], v[80:95]
	v_mfma_f32_32x32x16_bf16 v[80:95], v[144:147], v[234:237], v[80:95]
	v_mfma_f32_32x32x16_bf16 v[80:95], v[148:151], v[238:241], v[80:95]
	v_mfma_f32_32x32x16_bf16 v[80:95], v[152:155], v[242:245], v[80:95]
	v_mfma_f32_32x32x16_bf16 v[80:95], v[156:159], v[246:249], v[80:95]
	v_mfma_f32_32x32x16_bf16 v[80:95], v[160:163], v[250:253], v[80:95]
	s_waitcnt lgkmcnt(0)
	v_mfma_f32_32x32x16_bf16 v[80:95], v[164:167], v[212:215], v[80:95]
	s_cbranch_scc1 .LBB0_165
	s_nop 10
	v_cndmask_b32_e64 v211, v80, v226, s[8:9]
	v_cndmask_b32_e64 v81, v226, v81, s[10:11]
	v_cndmask_b32_e64 v80, v211, v80, s[10:11]
	v_cndmask_b32_e64 v82, v82, v226, s[12:13]
	v_cndmask_b32_e64 v83, v83, v226, s[14:15]
	v_cndmask_b32_e64 v84, v84, v226, s[16:17]
	v_cndmask_b32_e64 v85, v85, v226, s[18:19]
	v_cndmask_b32_e64 v86, v86, v226, s[20:21]
	v_cndmask_b32_e64 v87, v87, v226, s[22:23]
	v_cndmask_b32_e64 v88, v88, v226, s[24:25]
	v_cndmask_b32_e64 v89, v89, v226, s[26:27]
	v_cndmask_b32_e64 v90, v90, v226, s[28:29]
	v_cndmask_b32_e64 v91, v91, v226, s[30:31]
	v_cndmask_b32_e64 v92, v92, v226, s[34:35]
	v_cndmask_b32_e64 v93, v93, v226, s[36:37]
	v_cndmask_b32_e64 v94, v94, v226, s[38:39]
	v_cndmask_b32_e64 v95, v95, v226, s[40:41]

; #define LAS __attribute__((address_space(3)))
; __device__ __forceinline__ size_t vf_block(int b, int u, int tile) { return (size_t)((b * 16 + u) * 64 + tile) * 4096; }
; __device__ __forceinline__ size_t kfd_block(int b, int sk, int tile) { return (size_t)((b * 12 + sk) * 64 + tile) * 2048; }
; template <int DQ, bool QLDS, int KD  >
; __device__ __forceinline__ void attn_pass(const bf16_t* qrow  , const bf16_t* kbase  , const bf16_t* vbase  ,
;                                           int qt, int own, unsigned selmask, int r, int h, f32x16 (&O)[4], LAS unsigned char* wlds  ) {
;     ...
;     if constexpr (QLDS) {
; #pragma unroll
;         for (int ks = 0; ks < NKS; ++ks) *(LAS bf16x8*)(wlds + ks * 1024) = *(const bf16x8*)(qrow + 16 * ks);
; __device__ __forceinline__ void diff_task(const Ctx& c, ArgsP a, int l, int bh, int qt) {
;     const int b = bh / 6, hd = bh % 6, r = c.lane & 31, h = c.lane >> 5;
;     const bf16_t* proj = (const bf16_t*)(c.ws + WS_PROJ); const bf16_t* VT = (const bf16_t*)(c.ws + WS_VT); bf16_t* mix = (bf16_t*)(c.ws + WS_MIX);
;     const float* lf = a->in[5] + (size_t)l * 256;
;     const float d1 = wave_sum(lf[c.lane] * lf[64 + c.lane]), d2 = wave_sum(lf[128 + c.lane] * lf[192 + c.lane]);
;     const float lam_init = 0.8f - 0.6f * expf(-0.3f * (float)l);
;     const float lam = expf(d1) - expf(d2) + lam_init;
;     const size_t tokq = (size_t)b * SEQ + qt * 32 + r;
;     const bf16_t* kb = (const bf16_t*)(c.ws + WS_KFD) + kfd_block(b, hd * 2, 0) + c.lane * 8;
;     const bf16_t* vb = VT + vf_block(b, hd, 0) + c.lane * 8;
;     f32x16 O1[4];
;     LAS unsigned char* wl = c.lds + c.wave * 16384 + c.lane * 16;
;     {
;         f32x16 O2[4];
;         attn_pass<64, true, 2>(proj + tokq * PROJP + C_DQ + hd * 128 + 64 + 8 * h, kb + (size_t)64 * 2048, vb, qt, 0, 0u, r, h, O2, wl);
.LBB0_170:
	s_and_b64 vcc, exec, s[8:9]
	s_cbranch_vccz .LBB0_192
	s_mul_hi_i32 s2, s58, 0x2aaaaaab
	s_load_dwordx2 s[8:9], s[0:1], 0x28
	s_lshr_b32 s5, s2, 31
	s_add_i32 s10, s2, s5
	s_mul_i32 s2, s10, 6
	s_ashr_i32 s5, s4, 31
	s_sub_i32 s2, s58, s2
	s_lshl_b64 s[12:13], s[4:5], 10
	s_waitcnt lgkmcnt(0)
	s_add_u32 s8, s8, s12
	s_addc_u32 s9, s9, s13
	v_ashrrev_i32_e32 v201, 31, v200
	s_ashr_i32 s11, s10, 31
	v_lshl_add_u64 v[2:3], v[200:201], 2, s[8:9]
	s_lshl_b64 s[8:9], s[10:11], 11
	s_lshl_b32 s11, s92, 5
	v_and_b32_e32 v0, 31, v200
	s_add_u32 s8, s8, s11
	s_addc_u32 s14, s9, 0
	v_or_b32_e32 v202, s8, v0
	s_lshl_b32 s8, s58, 7
	s_ashr_i32 s9, s8, 31
	s_lshl_b64 s[8:9], s[8:9], 12
	global_load_dword v21, v[2:3], off
	global_load_dword v22, v[2:3], off offset:256
	global_load_dword v23, v[2:3], off offset:512
	global_load_dword v24, v[2:3], off offset:768
	s_add_u32 s8, s77, s8
	v_readlane_b32 s11, v255, 25
	s_addc_u32 s9, s11, s9
	s_lshl_b32 s10, s10, 10
	s_lshl_b32 s11, s2, 6
	s_add_i32 s10, s11, s10
	s_ashr_i32 s11, s10, 31
	s_lshl_b64 s[10:11], s[10:11], 13
	v_readlane_b32 s12, v255, 20
	s_add_u32 s10, s12, s10
	v_readlane_b32 s12, v255, 21
	v_mov_b64_e32 v[2:3], s[90:91]
	v_ashrrev_i32_e32 v20, 5, v200
	s_addc_u32 s11, s12, s11
	v_mad_u64_u32 v[2:3], s[12:13], v202, s53, v[2:3]
	v_mov_b32_e32 v4, 0x2080
	s_lshl_b32 s86, s2, 7
	v_mad_i32_i24 v3, s14, v4, v3
	s_ashr_i32 s87, s86, 31
	v_lshlrev_b32_e32 v4, 3, v20
	v_lshl_add_u64 v[2:3], s[86:87], 1, v[2:3]
	v_ashrrev_i32_e32 v5, 31, v4
	v_lshl_add_u64 v[216:217], v[4:5], 1, v[2:3]
	global_load_dwordx4 v[2:5], v[216:217], off offset:128
	global_load_dwordx4 v[6:9], v[216:217], off offset:160
	global_load_dwordx4 v[10:13], v[216:217], off offset:192
	global_load_dwordx4 v[14:17], v[216:217], off offset:224
	v_and_b32_e32 v19, 64, v225
	v_xor_b32_e32 v25, 1, v225
	v_add_u32_e32 v31, 64, v19
	v_xor_b32_e32 v26, 2, v225
	v_cmp_lt_i32_e32 vcc, v25, v31
	v_xor_b32_e32 v27, 4, v225
	v_xor_b32_e32 v28, 8, v225
	v_cndmask_b32_e32 v25, v225, v25, vcc
	v_cmp_lt_i32_e32 vcc, v26, v31
	v_xor_b32_e32 v29, 16, v225
	v_xor_b32_e32 v30, 32, v225
	v_cndmask_b32_e32 v26, v225, v26, vcc
	v_cmp_lt_i32_e32 vcc, v27, v31
	v_lshlrev_b32_e32 v25, 2, v25
	v_lshlrev_b32_e32 v26, 2, v26
	v_cndmask_b32_e32 v27, v225, v27, vcc
	v_cmp_lt_i32_e32 vcc, v28, v31
	s_mov_b32 s56, 0
	v_lshlrev_b32_e32 v18, 3, v200
	v_cndmask_b32_e32 v28, v225, v28, vcc
	v_cmp_lt_i32_e32 vcc, v29, v31
	v_lshl_add_u32 v205, v200, 4, s52
	v_ashrrev_i32_e32 v19, 31, v18
	v_cndmask_b32_e32 v29, v225, v29, vcc
	v_cmp_lt_i32_e32 vcc, v30, v31
	s_mov_b32 s58, s56
	s_mov_b32 s59, s56
	s_mov_b32 s57, s56
	v_lshlrev_b64 v[18:19], 1, v[18:19]
	v_mov_b64_e32 v[102:103], s[58:59]
	v_lshl_add_u64 v[206:207], s[8:9], 0, v[18:19]
	v_mov_b64_e32 v[100:101], s[56:57]
	v_mov_b64_e32 v[106:107], s[58:59]
	v_lshlrev_b32_e32 v27, 2, v27
	v_lshl_add_u64 v[218:219], v[206:207], 0, s[80:81]
	v_mov_b64_e32 v[104:105], s[56:57]
	v_mov_b64_e32 v[114:115], s[58:59]
	v_mov_b64_e32 v[112:113], s[56:57]
	v_mov_b64_e32 v[118:119], s[58:59]
	v_mov_b64_e32 v[116:117], s[56:57]
	v_mov_b64_e32 v[110:111], s[58:59]
	v_mov_b64_e32 v[108:109], s[56:57]
	v_mov_b64_e32 v[122:123], s[58:59]
	v_lshl_add_u64 v[208:209], s[10:11], 0, v[18:19]
	v_mov_b64_e32 v[120:121], s[56:57]
	v_mov_b64_e32 v[126:127], s[58:59]
	v_mov_b64_e32 v[124:125], s[56:57]
	v_mov_b64_e32 v[130:131], s[58:59]
	v_lshlrev_b32_e32 v28, 2, v28
	v_mov_b64_e32 v[128:129], s[56:57]
	v_mov_b64_e32 v[134:135], s[58:59]
	v_mov_b64_e32 v[132:133], s[56:57]
	s_waitcnt vmcnt(0)
	v_mul_f32_e32 v31, v21, v22
	ds_bpermute_b32 v31, v25, v31
	s_waitcnt vmcnt(4)
	v_mul_f32_e32 v32, v23, v24
	ds_bpermute_b32 v25, v25, v32
	s_waitcnt vmcnt(3)
	ds_write_b128 v205, v[2:5]
	s_waitcnt vmcnt(2)
	ds_write_b128 v205, v[6:9] offset:1024
	s_waitcnt lgkmcnt(3)
	v_fmac_f32_e32 v31, v21, v22
	s_waitcnt lgkmcnt(2)
	v_fmac_f32_e32 v25, v23, v24
	ds_bpermute_b32 v21, v26, v31
	ds_bpermute_b32 v22, v26, v25
	s_waitcnt vmcnt(1)
	ds_write_b128 v205, v[10:13] offset:2048
	s_waitcnt vmcnt(0)
	ds_write_b128 v205, v[14:17] offset:3072
	v_mov_b64_e32 v[236:237], v[2:3]
	v_mov_b64_e32 v[238:239], v[4:5]
	v_mov_b64_e32 v[240:241], v[6:7]
	v_mov_b64_e32 v[242:243], v[8:9]
	v_mov_b64_e32 v[244:245], v[10:11]
	v_mov_b64_e32 v[246:247], v[12:13]
	v_mov_b64_e32 v[248:249], v[14:15]
	v_mov_b64_e32 v[250:251], v[16:17]
	s_waitcnt vmcnt(0)
	global_load_dwordx4 v[100:103], v[218:219], off offset:0
	s_waitcnt lgkmcnt(3)
	v_add_f32_e32 v21, v31, v21
	s_waitcnt lgkmcnt(2)
	v_add_f32_e32 v22, v25, v22
	ds_bpermute_b32 v23, v27, v21
	ds_bpermute_b32 v24, v27, v22
	global_load_dwordx4 v[104:107], v[218:219], off offset:0x400
	global_load_dwordx4 v[112:115], v[218:219], off offset:0x800
	global_load_dwordx4 v[116:119], v[218:219], off offset:0xc00
	global_load_dwordx4 v[108:111], v[208:209], off offset:0
	global_load_dwordx4 v[120:123], v[208:209], off offset:0x400
	s_waitcnt lgkmcnt(1)
	v_add_f32_e32 v2, v21, v23
	s_waitcnt lgkmcnt(0)
; #define ATTN_NEXT(k) (((((k) + 1) & 7) == 0) ? ((k) + 1 + 8 * __builtin_ctz(bmask >> (((k) + 1) >> 3))) : ((k) + 1))
; template <int DQ, bool QLDS, int KD  >
; __device__ __forceinline__ void attn_pass(const bf16_t* qrow  , const bf16_t* kbase  , const bf16_t* vbase  ,
;                                           int qt, int own, unsigned selmask, int r, int h, f32x16 (&O)[4], LAS unsigned char* wlds  ) {
;     ...
;     for (int t = 0; t < 4; ++t)
; #pragma unroll
;         for (int i = 0; i < 16; ++i) O[t][i] = 0.f;
;     unsigned bmask = 0u;
;     for (int n = 0; n < own; ++n) if (__ballot((selmask >> n) & 1u) != 0ull) bmask |= 1u << n;
;     bmask |= 0xffffff00u | (0xffu & ~((1u << own) - 1u));
;     bmask = (unsigned)__builtin_amdgcn_readfirstlane((int)bmask);
;     float m = NEG_BIG, l = 0.f;
;     int kt = 8 * __builtin_ctz(bmask);
;     bf16x8 kfa[NKS], kfb[KD == 2 ? NKS : 1], vfa[8], vfb[8];
; #pragma unroll
;     for (int i = 0; i < NKS; ++i) { kfa[i] = (bf16x8){0, 0, 0, 0, 0, 0, 0, 0}; if constexpr (KD == 2) kfb[i] = (bf16x8){0, 0, 0, 0, 0, 0, 0, 0}; }
; #pragma unroll
;     for (int i = 0; i < 8; ++i) { vfa[i] = (bf16x8){0, 0, 0, 0, 0, 0, 0, 0}; vfb[i] = (bf16x8){0, 0, 0, 0, 0, 0, 0, 0}; }
;     if constexpr (!QLDS) {
; #pragma unroll
;         for (int ks = 0; ks < NKS; ++ks) asm volatile("" : "+v"(qf[ks]));
;     }
;     ...
;     int k1 = ATTN_NEXT(kt);
;     asm volatile("s_waitcnt vmcnt(0)" ::: "memory");
;     if constexpr (KD == 2) {
;         issue_k<NKS>(kfa, kbase + (size_t)kt * (NKS * 512));            issue_v(vfa, vbase + (size_t)kt * 4096);
;         issue_k<NKS>(kfb, kbase + (size_t)ATTN_CLAMP(k1) * (NKS * 512)); issue_v(vfb, vbase + (size_t)ATTN_CLAMP(k1) * 4096);
;     } else {
;         issue_v(vfa, vbase + (size_t)kt * 4096); issue_k<NKS>(kfa, kbase + (size_t)kt * (NKS * 512)); issue_v(vfb, vbase + (size_t)ATTN_CLAMP(k1) * 4096);
	v_add_f32_e32 v3, v22, v24
	global_load_dwordx4 v[124:127], v[208:209], off offset:0x800
	ds_bpermute_b32 v4, v28, v2
	ds_bpermute_b32 v5, v28, v3
	global_load_dwordx4 v[128:131], v[208:209], off offset:0xc00
	v_mov_b64_e32 v[138:139], s[58:59]
	v_lshl_add_u64 v[212:213], v[208:209], 0, s[78:79]
	global_load_dwordx4 v[132:135], v[212:213], off offset:0
	v_mov_b64_e32 v[136:137], s[56:57]
	v_mov_b64_e32 v[142:143], s[58:59]
	s_and_b32 s2, s92, 0xffff
	global_load_dwordx4 v[136:139], v[212:213], off offset:0x400
	v_mov_b64_e32 v[140:141], s[56:57]
	v_mov_b64_e32 v[146:147], s[58:59]
	s_cmp_eq_u32 s2, 0
	global_load_dwordx4 v[140:143], v[212:213], off offset:0x800
	v_mov_b64_e32 v[144:145], s[56:57]
	s_cselect_b32 s2, 0, 0x800
	v_mov_b64_e32 v[150:151], s[58:59]
	global_load_dwordx4 v[144:147], v[212:213], off offset:0xc00
	s_cselect_b32 s8, 0, 0x2000
	s_lshl_b32 s60, s2, 1
	v_mov_b64_e32 v[148:149], s[56:57]
	v_mov_b64_e32 v[154:155], s[58:59]
	s_waitcnt lgkmcnt(1)
	v_add_f32_e32 v230, v2, v4
	s_waitcnt lgkmcnt(0)
	v_add_f32_e32 v193, v3, v5
	v_lshl_add_u64 v[2:3], v[218:219], 0, s[60:61]
	global_load_dwordx4 v[148:151], v[2:3], off offset:0
	v_mov_b64_e32 v[152:153], s[56:57]
	v_mov_b64_e32 v[158:159], s[58:59]
	global_load_dwordx4 v[152:155], v[2:3], off offset:0x400
	v_mov_b64_e32 v[156:157], s[56:57]
	v_mov_b64_e32 v[166:167], s[58:59]
	global_load_dwordx4 v[156:159], v[2:3], off offset:0x800
	v_mov_b64_e32 v[164:165], s[56:57]
	v_lshlrev_b32_e32 v204, 2, v20
	global_load_dwordx4 v[164:167], v[2:3], off offset:0xc00
	v_or_b32_e32 v2, 2, v204
	v_cmp_gt_i32_e64 s[12:13], v2, v0
	v_or_b32_e32 v2, 3, v204
	v_mov_b32_e32 v203, s14
	v_cmp_gt_i32_e64 s[14:15], v2, v0
	v_add_u32_e32 v2, 8, v204
	v_cmp_gt_i32_e64 s[16:17], v2, v0
	v_add_u32_e32 v2, 9, v204
	v_mov_b64_e32 v[162:163], s[58:59]
	v_cmp_gt_i32_e64 s[18:19], v2, v0
	v_add_u32_e32 v2, 10, v204
	s_mov_b32 s9, s56
	v_mov_b64_e32 v[160:161], s[56:57]
	v_mov_b64_e32 v[170:171], s[58:59]
	v_cmp_gt_i32_e64 s[20:21], v2, v0
	v_add_u32_e32 v2, 11, v204
	v_lshl_add_u64 v[214:215], v[208:209], 0, s[8:9]
	global_load_dwordx4 v[160:163], v[214:215], off offset:0
	v_mov_b64_e32 v[168:169], s[56:57]
	v_mov_b64_e32 v[174:175], s[58:59]
	v_cmp_gt_i32_e64 s[22:23], v2, v0
	v_add_u32_e32 v2, 16, v204
	global_load_dwordx4 v[168:171], v[214:215], off offset:0x400
	v_mov_b64_e32 v[172:173], s[56:57]
	v_mov_b64_e32 v[178:179], s[58:59]
	v_cmp_gt_i32_e64 s[24:25], v2, v0
	v_add_u32_e32 v2, 17, v204
	global_load_dwordx4 v[172:175], v[214:215], off offset:0x800
	v_mov_b64_e32 v[176:177], s[56:57]
	v_mov_b64_e32 v[182:183], s[58:59]
	v_cmp_gt_i32_e64 s[26:27], v2, v0
	v_add_u32_e32 v2, 18, v204
	global_load_dwordx4 v[176:179], v[214:215], off offset:0xc00
	v_mov_b64_e32 v[180:181], s[56:57]
	v_mov_b64_e32 v[186:187], s[58:59]
	v_cmp_gt_i32_e64 s[28:29], v2, v0
	v_add_u32_e32 v2, 19, v204
	v_lshlrev_b32_e32 v29, 2, v29
	v_lshl_add_u64 v[210:211], v[214:215], 0, s[78:79]
	global_load_dwordx4 v[180:183], v[210:211], off offset:0
	v_mov_b64_e32 v[184:185], s[56:57]
	v_mov_b64_e32 v[190:191], s[58:59]
	v_cmp_gt_i32_e64 s[30:31], v2, v0
	v_add_u32_e32 v2, 24, v204
	v_mov_b64_e32 v[98:99], s[58:59]
	ds_bpermute_b32 v231, v29, v230
	ds_bpermute_b32 v229, v29, v193
	global_load_dwordx4 v[184:187], v[210:211], off offset:0x400
	v_mov_b64_e32 v[188:189], s[56:57]
	v_cmp_gt_i32_e64 s[34:35], v2, v0
	v_add_u32_e32 v2, 25, v204
	v_mov_b64_e32 v[96:97], s[56:57]
	global_load_dwordx4 v[188:191], v[210:211], off offset:0x800
	v_cmp_gt_i32_e64 s[36:37], v2, v0
	v_add_u32_e32 v2, 26, v204
	v_cndmask_b32_e32 v30, v225, v30, vcc
	global_load_dwordx4 v[96:99], v[210:211], off offset:0xc00
	v_cmp_gt_i32_e64 s[38:39], v2, v0
	v_add_u32_e32 v2, 27, v204
	v_mov_b32_e32 v14, v1
	v_mov_b32_e32 v15, v1
	v_lshlrev_b32_e32 v201, 2, v30
	v_cmp_gt_i32_e64 s[8:9], v204, v0
	v_cmp_lt_i32_e64 s[10:11], v204, v0
	v_cmp_gt_i32_e64 s[40:41], v2, v0
	v_mov_b32_e32 v0, v1
	v_mov_b32_e32 v2, v1
	v_mov_b32_e32 v3, v1
	v_mov_b32_e32 v4, v1
	v_mov_b32_e32 v5, v1
	v_mov_b32_e32 v6, v1
	v_mov_b32_e32 v7, v1
	v_mov_b32_e32 v8, v1
	v_mov_b32_e32 v9, v1
	v_mov_b32_e32 v10, v1
	v_mov_b32_e32 v11, v1
	v_mov_b32_e32 v12, v1
	v_mov_b32_e32 v13, v1
	v_mov_b64_e32 v[30:31], v[14:15]
	v_mov_b64_e32 v[46:47], v[14:15]
	v_mov_b64_e32 v[62:63], v[14:15]
	v_mov_b64_e32 v[78:79], v[14:15]
	v_mov_b32_e32 v232, 0xf149f2ca
	v_mov_b32_e32 v233, 0
	v_mov_b64_e32 v[28:29], v[12:13]
	v_mov_b64_e32 v[26:27], v[10:11]
	v_mov_b64_e32 v[24:25], v[8:9]
	v_mov_b64_e32 v[22:23], v[6:7]
	v_mov_b64_e32 v[20:21], v[4:5]
	v_mov_b64_e32 v[18:19], v[2:3]
	v_mov_b64_e32 v[16:17], v[0:1]
	v_mov_b64_e32 v[44:45], v[12:13]
	v_mov_b64_e32 v[42:43], v[10:11]
	v_mov_b64_e32 v[40:41], v[8:9]
	v_mov_b64_e32 v[38:39], v[6:7]
	v_mov_b64_e32 v[36:37], v[4:5]
	v_mov_b64_e32 v[34:35], v[2:3]
	v_mov_b64_e32 v[32:33], v[0:1]
	v_mov_b64_e32 v[60:61], v[12:13]
	v_mov_b64_e32 v[58:59], v[10:11]
	v_mov_b64_e32 v[56:57], v[8:9]
	v_mov_b64_e32 v[54:55], v[6:7]
	v_mov_b64_e32 v[52:53], v[4:5]
	v_mov_b64_e32 v[50:51], v[2:3]
	v_mov_b64_e32 v[48:49], v[0:1]
	v_mov_b64_e32 v[76:77], v[12:13]
	v_mov_b64_e32 v[74:75], v[10:11]
	v_mov_b64_e32 v[72:73], v[8:9]
	v_mov_b64_e32 v[70:71], v[6:7]
	v_mov_b64_e32 v[68:69], v[4:5]
	v_mov_b64_e32 v[66:67], v[2:3]
	v_mov_b64_e32 v[64:65], v[0:1]
	s_branch .LBB0_173

.LBB0_173:
	s_waitcnt vmcnt(20)
	s_cmp_lg_u32 s92, s56
	v_mfma_f32_32x32x16_bf16 v[80:95], v[100:103], v[236:239], 0
	v_mfma_f32_32x32x16_bf16 v[80:95], v[104:107], v[240:243], v[80:95]
	v_mfma_f32_32x32x16_bf16 v[80:95], v[112:115], v[244:247], v[80:95]
	v_mfma_f32_32x32x16_bf16 v[80:95], v[116:119], v[248:251], v[80:95]
	s_cbranch_scc1 .LBB0_175
	s_nop 10
	v_cndmask_b32_e64 v0, v80, v226, s[8:9]
	v_cndmask_b32_e64 v81, v226, v81, s[10:11]
	v_cndmask_b32_e64 v80, v0, v80, s[10:11]
	v_cndmask_b32_e64 v82, v82, v226, s[12:13]
	v_cndmask_b32_e64 v83, v83, v226, s[14:15]
	v_cndmask_b32_e64 v84, v84, v226, s[16:17]
	v_cndmask_b32_e64 v85, v85, v226, s[18:19]
	v_cndmask_b32_e64 v86, v86, v226, s[20:21]
	v_cndmask_b32_e64 v87, v87, v226, s[22:23]
	v_cndmask_b32_e64 v88, v88, v226, s[24:25]
	v_cndmask_b32_e64 v89, v89, v226, s[26:27]
	v_cndmask_b32_e64 v90, v90, v226, s[28:29]
	v_cndmask_b32_e64 v91, v91, v226, s[30:31]
	v_cndmask_b32_e64 v92, v92, v226, s[34:35]
	v_cndmask_b32_e64 v93, v93, v226, s[36:37]
	v_cndmask_b32_e64 v94, v94, v226, s[38:39]
	v_cndmask_b32_e64 v95, v95, v226, s[40:41]

.LBB0_177:
	s_add_i32 s42, s56, 2
	s_min_u32 s42, s42, s92
	s_lshl_b32 s60, s42, 12
	v_lshl_add_u64 v[2:3], v[218:219], 0, s[60:61]
	global_load_dwordx4 v[100:103], v[2:3], off offset:0
	global_load_dwordx4 v[104:107], v[2:3], off offset:0x400
	global_load_dwordx4 v[112:115], v[2:3], off offset:0x800
	global_load_dwordx4 v[116:119], v[2:3], off offset:0xc00
	v_sub_f32_e32 v0, v80, v232
	v_sub_f32_e32 v2, v81, v232
	v_sub_f32_e32 v3, v82, v232
	v_sub_f32_e32 v4, v83, v232
	v_sub_f32_e32 v5, v84, v232
	v_sub_f32_e32 v6, v85, v232
	v_sub_f32_e32 v7, v86, v232
	v_sub_f32_e32 v8, v87, v232
	v_exp_f32_e32 v0, v0
	v_exp_f32_e32 v2, v2
	v_exp_f32_e32 v3, v3
	v_exp_f32_e32 v4, v4
	v_exp_f32_e32 v5, v5
	v_exp_f32_e32 v6, v6
	v_exp_f32_e32 v7, v7
	v_exp_f32_e32 v9, v8
	v_sub_f32_e32 v80, v95, v232
	v_exp_f32_e32 v234, v80
	v_cvt_pk_bf16_f32 v80, v0, v2
	v_cvt_pk_bf16_f32 v81, v3, v4
	v_cvt_pk_bf16_f32 v82, v5, v6
	v_cvt_pk_bf16_f32 v83, v7, v9
	s_waitcnt vmcnt(16)
	v_sub_f32_e32 v12, v91, v232
	v_sub_f32_e32 v8, v88, v232
	v_mfma_f32_32x32x16_bf16 v[64:79], v[108:111], v[80:83], v[64:79]
	v_sub_f32_e32 v10, v89, v232
	v_sub_f32_e32 v11, v90, v232
	v_exp_f32_e32 v13, v12
	v_sub_f32_e32 v12, v92, v232
	v_sub_f32_e32 v14, v93, v232
	v_sub_f32_e32 v15, v94, v232
	v_exp_f32_e32 v8, v8
	v_mfma_f32_32x32x16_bf16 v[48:63], v[124:127], v[80:83], v[48:63]
	v_exp_f32_e32 v10, v10
	v_exp_f32_e32 v11, v11
	v_exp_f32_e32 v12, v12
	v_exp_f32_e32 v14, v14
	v_exp_f32_e32 v15, v15
	v_cvt_pk_bf16_f32 v84, v8, v10
	v_cvt_pk_bf16_f32 v85, v11, v13
	v_mfma_f32_32x32x16_bf16 v[32:47], v[132:135], v[80:83], v[32:47]
	v_cvt_pk_bf16_f32 v86, v12, v14
	v_cvt_pk_bf16_f32 v87, v15, v234
	s_lshl_b32 s60, s42, 13
	v_mov_b32_e32 v220, v205
	s_add_i32 s57, s56, 1
	s_cmp_lg_u32 s57, s92
	v_mfma_f32_32x32x16_bf16 v[16:31], v[140:143], v[80:83], v[16:31]
	v_lshl_add_u64 v[80:81], v[208:209], 0, s[60:61]
	v_lshl_add_u64 v[82:83], v[80:81], 0, s[78:79]
	v_mfma_f32_32x32x16_bf16 v[64:79], v[120:123], v[84:87], v[64:79]
	v_mfma_f32_32x32x16_bf16 v[48:63], v[128:131], v[84:87], v[48:63]
	v_mfma_f32_32x32x16_bf16 v[32:47], v[136:139], v[84:87], v[32:47]
	v_mfma_f32_32x32x16_bf16 v[16:31], v[144:147], v[84:87], v[16:31]
	global_load_dwordx4 v[108:111], v[80:81], off offset:0
	global_load_dwordx4 v[120:123], v[80:81], off offset:0x400
	global_load_dwordx4 v[124:127], v[80:81], off offset:0x800
	global_load_dwordx4 v[128:131], v[80:81], off offset:0xc00
	global_load_dwordx4 v[132:135], v[82:83], off offset:0
	global_load_dwordx4 v[136:139], v[82:83], off offset:0x400
	global_load_dwordx4 v[140:143], v[82:83], off offset:0x800
	global_load_dwordx4 v[144:147], v[82:83], off offset:0xc00
	s_waitcnt vmcnt(20)
	v_mfma_f32_32x32x16_bf16 v[80:95], v[148:151], v[236:239], 0
	v_mfma_f32_32x32x16_bf16 v[80:95], v[152:155], v[240:243], v[80:95]
	v_mfma_f32_32x32x16_bf16 v[80:95], v[156:159], v[244:247], v[80:95]
	v_mfma_f32_32x32x16_bf16 v[80:95], v[164:167], v[248:251], v[80:95]
	s_cbranch_scc1 .LBB0_179
	s_nop 10
	v_cndmask_b32_e64 v220, v80, v226, s[8:9]
	v_cndmask_b32_e64 v81, v226, v81, s[10:11]
	v_cndmask_b32_e64 v80, v220, v80, s[10:11]
	v_cndmask_b32_e64 v82, v82, v226, s[12:13]
	v_cndmask_b32_e64 v83, v83, v226, s[14:15]
	v_cndmask_b32_e64 v84, v84, v226, s[16:17]
	v_cndmask_b32_e64 v85, v85, v226, s[18:19]
	v_cndmask_b32_e64 v86, v86, v226, s[20:21]
	v_cndmask_b32_e64 v87, v87, v226, s[22:23]
	v_cndmask_b32_e64 v88, v88, v226, s[24:25]
	v_cndmask_b32_e64 v89, v89, v226, s[26:27]
	v_cndmask_b32_e64 v90, v90, v226, s[28:29]
	v_cndmask_b32_e64 v91, v91, v226, s[30:31]
	v_cndmask_b32_e64 v92, v92, v226, s[34:35]
	v_cndmask_b32_e64 v93, v93, v226, s[36:37]
	v_cndmask_b32_e64 v94, v94, v226, s[38:39]
	v_cndmask_b32_e64 v95, v95, v226, s[40:41]

; template <int DQ, bool QLDS, int KD  >
; __device__ __forceinline__ void attn_pass(const bf16_t* qrow  , const bf16_t* kbase  , const bf16_t* vbase  ,
;                                           int qt, int own, unsigned selmask, int r, int h, f32x16 (&O)[4], LAS unsigned char* wlds  ) {
;     ...
;     asm volatile("s_waitcnt vmcnt(0)" : "+v"(kfa[0]), "+v"(vfa[0]), "+v"(vfb[0]) :: "memory");
;     l += __shfl_xor(l, 32);
;     const float inv = 1.f / l;
; #pragma unroll
;     for (int t = 0; t < 4; ++t) O[t] = O[t] * inv;
; }
; __device__ __forceinline__ void store_o(bf16_t* orow  , const f32x16 (&O)[4]) {
; #pragma unroll
;     for (int t = 0; t < 4; ++t)
; #pragma unroll
;         for (int q = 0; q < 4; ++q) { u32x2 w; w.x = pk_bf16(O[t][4 * q], O[t][4 * q + 1]); w.y = pk_bf16(O[t][4 * q + 2], O[t][4 * q + 3]); *(u32x2*)(orow + 32 * t + 8 * q) = w; }
; }
; __device__ __forceinline__ void diff_task(const Ctx& c, ArgsP a, int l, int bh, int qt) {
;     const int b = bh / 6, hd = bh % 6, r = c.lane & 31, h = c.lane >> 5;
;     const bf16_t* proj = (const bf16_t*)(c.ws + WS_PROJ); const bf16_t* VT = (const bf16_t*)(c.ws + WS_VT); bf16_t* mix = (bf16_t*)(c.ws + WS_MIX);
;     const float* lf = a->in[5] + (size_t)l * 256;
;     const float d1 = wave_sum(lf[c.lane] * lf[64 + c.lane]), d2 = wave_sum(lf[128 + c.lane] * lf[192 + c.lane]);
;     const float lam_init = 0.8f - 0.6f * expf(-0.3f * (float)l);
;     const float lam = expf(d1) - expf(d2) + lam_init;
;     const size_t tokq = (size_t)b * SEQ + qt * 32 + r;
;     const bf16_t* kb = (const bf16_t*)(c.ws + WS_KFD) + kfd_block(b, hd * 2, 0) + c.lane * 8;
;     const bf16_t* vb = VT + vf_block(b, hd, 0) + c.lane * 8;
;     f32x16 O1[4];
;     LAS unsigned char* wl = c.lds + c.wave * 16384 + c.lane * 16;
;     {
;         f32x16 O2[4];
;         attn_pass<64, true, 2>(proj + tokq * PROJP + C_DQ + hd * 128 + 64 + 8 * h, kb + (size_t)64 * 2048, vb, qt, 0, 0u, r, h, O2, wl);
; #pragma unroll
;         for (int t = 0; t < 4; ++t)
; #pragma unroll
;             for (int hf = 0; hf < 2; ++hf) { u32x4 w; w.x = pk_bf16(O2[t][8 * hf], O2[t][8 * hf + 1]); w.y = pk_bf16(O2[t][8 * hf + 2], O2[t][8 * hf + 3]); w.z = pk_bf16(O2[t][8 * hf + 4], O2[t][8 * hf + 5]); w.w = pk_bf16(O2[t][8 * hf + 6], O2[t][8 * hf + 7]);
;                 *(LAS u32x4*)(wl + 8192 + (t * 2 + hf) * 1024) = w; }
;     }
.LBB0_181:
	ds_bpermute_b32 v0, v201, v233
	s_waitcnt vmcnt(0)
	global_load_dwordx4 v[2:5], v[216:217], off
	global_load_dwordx4 v[6:9], v[216:217], off offset:32
	s_mov_b32 s56, 0
	s_mov_b32 s58, s56
	s_waitcnt lgkmcnt(0)
	v_add_f32_e32 v0, v233, v0
	v_div_scale_f32 v14, s[42:43], v0, v0, 1.0
	v_rcp_f32_e32 v15, v14
	v_div_scale_f32 v84, vcc, 1.0, v0, 1.0
	s_mov_b32 s59, s56
	v_fma_f32 v10, -v14, v15, 1.0
	v_fmac_f32_e32 v15, v10, v15
	v_mul_f32_e32 v85, v84, v15
	v_fma_f32 v10, -v14, v85, v84
	v_fmac_f32_e32 v85, v10, v15
	global_load_dwordx4 v[10:13], v[216:217], off offset:64
	global_load_dwordx4 v[80:83], v[216:217], off offset:96
	v_fma_f32 v14, -v14, v85, v84
	v_div_fmas_f32 v14, v14, v15, v85
	v_div_fixup_f32 v0, v14, v0, 1.0
	v_pk_mul_f32 v[70:71], v[70:71], v[0:1] op_sel_hi:[1,0]
	v_pk_mul_f32 v[68:69], v[68:69], v[0:1] op_sel_hi:[1,0]
	v_pk_mul_f32 v[66:67], v[66:67], v[0:1] op_sel_hi:[1,0]
	v_pk_mul_f32 v[14:15], v[64:65], v[0:1] op_sel_hi:[1,0]
	v_pk_mul_f32 v[78:79], v[78:79], v[0:1] op_sel_hi:[1,0]
	v_pk_mul_f32 v[76:77], v[76:77], v[0:1] op_sel_hi:[1,0]
	v_pk_mul_f32 v[74:75], v[74:75], v[0:1] op_sel_hi:[1,0]
	v_pk_mul_f32 v[72:73], v[72:73], v[0:1] op_sel_hi:[1,0]
	v_pk_mul_f32 v[64:65], v[16:17], v[0:1] op_sel_hi:[1,0]
	v_cvt_pk_bf16_f32 v14, v14, v15
	v_cvt_pk_bf16_f32 v15, v66, v67
	v_cvt_pk_bf16_f32 v16, v68, v69
	v_cvt_pk_bf16_f32 v17, v70, v71
	v_pk_mul_f32 v[54:55], v[54:55], v[0:1] op_sel_hi:[1,0]
	v_pk_mul_f32 v[52:53], v[52:53], v[0:1] op_sel_hi:[1,0]
	v_pk_mul_f32 v[50:51], v[50:51], v[0:1] op_sel_hi:[1,0]
	v_pk_mul_f32 v[48:49], v[48:49], v[0:1] op_sel_hi:[1,0]
	ds_write_b128 v205, v[14:17] offset:8192
	v_cvt_pk_bf16_f32 v14, v72, v73
	v_cvt_pk_bf16_f32 v15, v74, v75
	v_cvt_pk_bf16_f32 v16, v76, v77
	v_cvt_pk_bf16_f32 v17, v78, v79
	v_pk_mul_f32 v[62:63], v[62:63], v[0:1] op_sel_hi:[1,0]
	v_pk_mul_f32 v[60:61], v[60:61], v[0:1] op_sel_hi:[1,0]
	v_pk_mul_f32 v[58:59], v[58:59], v[0:1] op_sel_hi:[1,0]
	v_pk_mul_f32 v[56:57], v[56:57], v[0:1] op_sel_hi:[1,0]
	ds_write_b128 v205, v[14:17] offset:9216
	v_cvt_pk_bf16_f32 v14, v48, v49
	v_cvt_pk_bf16_f32 v15, v50, v51
	v_cvt_pk_bf16_f32 v16, v52, v53
	v_cvt_pk_bf16_f32 v17, v54, v55
	v_pk_mul_f32 v[38:39], v[38:39], v[0:1] op_sel_hi:[1,0]
	v_pk_mul_f32 v[36:37], v[36:37], v[0:1] op_sel_hi:[1,0]
	v_pk_mul_f32 v[34:35], v[34:35], v[0:1] op_sel_hi:[1,0]
	v_pk_mul_f32 v[32:33], v[32:33], v[0:1] op_sel_hi:[1,0]
	ds_write_b128 v205, v[14:17] offset:10240
	v_cvt_pk_bf16_f32 v14, v56, v57
	v_cvt_pk_bf16_f32 v15, v58, v59
	v_cvt_pk_bf16_f32 v16, v60, v61
	v_cvt_pk_bf16_f32 v17, v62, v63
	v_pk_mul_f32 v[46:47], v[46:47], v[0:1] op_sel_hi:[1,0]
	v_pk_mul_f32 v[44:45], v[44:45], v[0:1] op_sel_hi:[1,0]
	v_pk_mul_f32 v[42:43], v[42:43], v[0:1] op_sel_hi:[1,0]
	v_pk_mul_f32 v[40:41], v[40:41], v[0:1] op_sel_hi:[1,0]
	ds_write_b128 v205, v[14:17] offset:11264
	v_cvt_pk_bf16_f32 v14, v32, v33
	v_cvt_pk_bf16_f32 v15, v34, v35
	v_cvt_pk_bf16_f32 v16, v36, v37
	v_cvt_pk_bf16_f32 v17, v38, v39
	v_pk_mul_f32 v[22:23], v[22:23], v[0:1] op_sel_hi:[1,0]
	v_pk_mul_f32 v[20:21], v[20:21], v[0:1] op_sel_hi:[1,0]
	v_pk_mul_f32 v[18:19], v[18:19], v[0:1] op_sel_hi:[1,0]
	ds_write_b128 v205, v[14:17] offset:12288
	v_cvt_pk_bf16_f32 v14, v40, v41
	v_cvt_pk_bf16_f32 v15, v42, v43
	v_cvt_pk_bf16_f32 v16, v44, v45
	v_cvt_pk_bf16_f32 v17, v46, v47
	v_pk_mul_f32 v[30:31], v[30:31], v[0:1] op_sel_hi:[1,0]
	v_pk_mul_f32 v[28:29], v[28:29], v[0:1] op_sel_hi:[1,0]
	v_pk_mul_f32 v[26:27], v[26:27], v[0:1] op_sel_hi:[1,0]
	v_pk_mul_f32 v[24:25], v[24:25], v[0:1] op_sel_hi:[1,0]
	ds_write_b128 v205, v[14:17] offset:13312
	v_cvt_pk_bf16_f32 v14, v64, v65
	v_cvt_pk_bf16_f32 v15, v18, v19
	v_cvt_pk_bf16_f32 v16, v20, v21
	v_cvt_pk_bf16_f32 v17, v22, v23
	ds_write_b128 v205, v[14:17] offset:14336
	v_cvt_pk_bf16_f32 v14, v24, v25
	v_cvt_pk_bf16_f32 v15, v26, v27
	v_cvt_pk_bf16_f32 v16, v28, v29
	v_cvt_pk_bf16_f32 v17, v30, v31
	s_mov_b32 s57, s56
	v_mov_b64_e32 v[98:99], s[58:59]
	v_mov_b64_e32 v[96:97], s[56:57]
	ds_write_b128 v205, v[14:17] offset:15360
	s_waitcnt vmcnt(3)
	ds_write_b128 v205, v[2:5]
	s_waitcnt vmcnt(2)
	ds_write_b128 v205, v[6:9] offset:1024
	s_waitcnt vmcnt(1)
	ds_write_b128 v205, v[10:13] offset:2048
	s_waitcnt vmcnt(0)
	ds_write_b128 v205, v[80:83] offset:3072
	v_mov_b64_e32 v[236:237], v[2:3]
	v_mov_b64_e32 v[238:239], v[4:5]
	v_mov_b64_e32 v[240:241], v[6:7]
	v_mov_b64_e32 v[242:243], v[8:9]
	v_mov_b64_e32 v[244:245], v[10:11]
	v_mov_b64_e32 v[246:247], v[12:13]
	v_mov_b64_e32 v[248:249], v[80:81]
	v_mov_b64_e32 v[250:251], v[82:83]
	s_waitcnt vmcnt(0)
; #define ATTN_NEXT(k) (((((k) + 1) & 7) == 0) ? ((k) + 1 + 8 * __builtin_ctz(bmask >> (((k) + 1) >> 3))) : ((k) + 1))
; template <int DQ, bool QLDS, int KD  >
; __device__ __forceinline__ void attn_pass(const bf16_t* qrow  , const bf16_t* kbase  , const bf16_t* vbase  ,
;                                           int qt, int own, unsigned selmask, int r, int h, f32x16 (&O)[4], LAS unsigned char* wlds  ) {
;     ...
;     for (int t = 0; t < 4; ++t)
; #pragma unroll
;         for (int i = 0; i < 16; ++i) O[t][i] = 0.f;
;     unsigned bmask = 0u;
;     for (int n = 0; n < own; ++n) if (__ballot((selmask >> n) & 1u) != 0ull) bmask |= 1u << n;
;     bmask |= 0xffffff00u | (0xffu & ~((1u << own) - 1u));
;     bmask = (unsigned)__builtin_amdgcn_readfirstlane((int)bmask);
;     float m = NEG_BIG, l = 0.f;
;     int kt = 8 * __builtin_ctz(bmask);
;     bf16x8 kfa[NKS], kfb[KD == 2 ? NKS : 1], vfa[8], vfb[8];
; #pragma unroll
;     for (int i = 0; i < NKS; ++i) { kfa[i] = (bf16x8){0, 0, 0, 0, 0, 0, 0, 0}; if constexpr (KD == 2) kfb[i] = (bf16x8){0, 0, 0, 0, 0, 0, 0, 0}; }
; #pragma unroll
;     for (int i = 0; i < 8; ++i) { vfa[i] = (bf16x8){0, 0, 0, 0, 0, 0, 0, 0}; vfb[i] = (bf16x8){0, 0, 0, 0, 0, 0, 0, 0}; }
;     if constexpr (!QLDS) {
; #pragma unroll
;         for (int ks = 0; ks < NKS; ++ks) asm volatile("" : "+v"(qf[ks]));
;     }
;     ...
;     int k1 = ATTN_NEXT(kt);
;     asm volatile("s_waitcnt vmcnt(0)" ::: "memory");
;     if constexpr (KD == 2) {
;         issue_k<NKS>(kfa, kbase + (size_t)kt * (NKS * 512));            issue_v(vfa, vbase + (size_t)kt * 4096);
;         issue_k<NKS>(kfb, kbase + (size_t)ATTN_CLAMP(k1) * (NKS * 512)); issue_v(vfb, vbase + (size_t)ATTN_CLAMP(k1) * 4096);
;     } else {
;         issue_v(vfa, vbase + (size_t)kt * 4096); issue_k<NKS>(kfa, kbase + (size_t)kt * (NKS * 512)); issue_v(vfb, vbase + (size_t)ATTN_CLAMP(k1) * 4096);
	v_mov_b64_e32 v[114:115], s[58:59]
	global_load_dwordx4 v[96:99], v[206:207], off offset:0
	v_mov_b64_e32 v[112:113], s[56:57]
	v_mov_b64_e32 v[118:119], s[58:59]
	global_load_dwordx4 v[112:115], v[206:207], off offset:0x400
	v_mov_b64_e32 v[116:117], s[56:57]
	v_mov_b64_e32 v[122:123], s[58:59]
	global_load_dwordx4 v[116:119], v[206:207], off offset:0x800
	v_mov_b64_e32 v[120:121], s[56:57]
	v_mov_b64_e32 v[102:103], s[58:59]
	global_load_dwordx4 v[120:123], v[206:207], off offset:0xc00
	v_mov_b64_e32 v[100:101], s[56:57]
	v_mov_b64_e32 v[126:127], s[58:59]
	global_load_dwordx4 v[100:103], v[208:209], off offset:0
	v_mov_b64_e32 v[124:125], s[56:57]
	v_mov_b64_e32 v[130:131], s[58:59]
	global_load_dwordx4 v[124:127], v[208:209], off offset:0x400
	v_mov_b64_e32 v[128:129], s[56:57]
	v_mov_b64_e32 v[134:135], s[58:59]
	global_load_dwordx4 v[128:131], v[208:209], off offset:0x800
	v_mov_b64_e32 v[132:133], s[56:57]
	v_mov_b64_e32 v[138:139], s[58:59]
	global_load_dwordx4 v[132:135], v[208:209], off offset:0xc00
	v_mov_b64_e32 v[136:137], s[56:57]
	v_mov_b64_e32 v[142:143], s[58:59]
	global_load_dwordx4 v[136:139], v[212:213], off offset:0
	v_mov_b64_e32 v[140:141], s[56:57]
	v_mov_b64_e32 v[146:147], s[58:59]
	global_load_dwordx4 v[140:143], v[212:213], off offset:0x400
	v_mov_b64_e32 v[144:145], s[56:57]
	v_mov_b64_e32 v[150:151], s[58:59]
	global_load_dwordx4 v[144:147], v[212:213], off offset:0x800
	v_mov_b64_e32 v[148:149], s[56:57]
	v_mov_b64_e32 v[154:155], s[58:59]
	global_load_dwordx4 v[148:151], v[212:213], off offset:0xc00
	s_lshl_b32 s60, s2, 1
	v_mov_b64_e32 v[152:153], s[56:57]
	v_mov_b64_e32 v[158:159], s[58:59]
	v_lshl_add_u64 v[2:3], v[206:207], 0, s[60:61]
	global_load_dwordx4 v[152:155], v[2:3], off offset:0
	v_mov_b64_e32 v[156:157], s[56:57]
	v_mov_b64_e32 v[162:163], s[58:59]
	global_load_dwordx4 v[156:159], v[2:3], off offset:0x400
	v_mov_b64_e32 v[160:161], s[56:57]
	v_mov_b64_e32 v[166:167], s[58:59]
	global_load_dwordx4 v[160:163], v[2:3], off offset:0x800
	v_mov_b64_e32 v[164:165], s[56:57]
	v_mov_b64_e32 v[106:107], s[58:59]
	global_load_dwordx4 v[164:167], v[2:3], off offset:0xc00
	v_mov_b64_e32 v[104:105], s[56:57]
	v_mov_b64_e32 v[170:171], s[58:59]
	global_load_dwordx4 v[104:107], v[214:215], off offset:0
	v_mov_b64_e32 v[168:169], s[56:57]
	v_mov_b64_e32 v[174:175], s[58:59]
	global_load_dwordx4 v[168:171], v[214:215], off offset:0x400
	v_mov_b64_e32 v[172:173], s[56:57]
	v_mov_b64_e32 v[178:179], s[58:59]
	global_load_dwordx4 v[172:175], v[214:215], off offset:0x800
	v_mov_b64_e32 v[176:177], s[56:57]
	v_mov_b64_e32 v[182:183], s[58:59]
	global_load_dwordx4 v[176:179], v[214:215], off offset:0xc00
	v_mov_b64_e32 v[180:181], s[56:57]
	v_mov_b64_e32 v[186:187], s[58:59]
	global_load_dwordx4 v[180:183], v[210:211], off offset:0
	v_mov_b64_e32 v[184:185], s[56:57]
	v_mov_b64_e32 v[190:191], s[58:59]
	v_mov_b64_e32 v[110:111], s[58:59]
	global_load_dwordx4 v[184:187], v[210:211], off offset:0x400
	v_mov_b64_e32 v[188:189], s[56:57]
	v_mov_b64_e32 v[108:109], s[56:57]
	global_load_dwordx4 v[188:191], v[210:211], off offset:0x800
	global_load_dwordx4 v[108:111], v[210:211], off offset:0xc00
	v_mov_b32_e32 v14, v1
	v_mov_b32_e32 v15, v1
	v_mov_b32_e32 v0, v1
	v_mov_b32_e32 v2, v1
	v_mov_b32_e32 v3, v1
	v_mov_b32_e32 v4, v1
	v_mov_b32_e32 v5, v1
	v_mov_b32_e32 v6, v1
	v_mov_b32_e32 v7, v1
	v_mov_b32_e32 v8, v1
	v_mov_b32_e32 v9, v1
	v_mov_b32_e32 v10, v1
	v_mov_b32_e32 v11, v1
	v_mov_b32_e32 v12, v1
	v_mov_b32_e32 v13, v1
	v_mov_b64_e32 v[30:31], v[14:15]
	v_mov_b64_e32 v[46:47], v[14:15]
	v_mov_b64_e32 v[62:63], v[14:15]
	v_mov_b64_e32 v[78:79], v[14:15]
	v_mov_b32_e32 v210, 0xf149f2ca
	v_mov_b32_e32 v211, 0
	v_mov_b64_e32 v[28:29], v[12:13]
	v_mov_b64_e32 v[26:27], v[10:11]
	v_mov_b64_e32 v[24:25], v[8:9]
	v_mov_b64_e32 v[22:23], v[6:7]
	v_mov_b64_e32 v[20:21], v[4:5]
	v_mov_b64_e32 v[18:19], v[2:3]
	v_mov_b64_e32 v[16:17], v[0:1]
	v_mov_b64_e32 v[44:45], v[12:13]
	v_mov_b64_e32 v[42:43], v[10:11]
	v_mov_b64_e32 v[40:41], v[8:9]
	v_mov_b64_e32 v[38:39], v[6:7]
	v_mov_b64_e32 v[36:37], v[4:5]
	v_mov_b64_e32 v[34:35], v[2:3]
	v_mov_b64_e32 v[32:33], v[0:1]
	v_mov_b64_e32 v[60:61], v[12:13]
	v_mov_b64_e32 v[58:59], v[10:11]
	v_mov_b64_e32 v[56:57], v[8:9]
	v_mov_b64_e32 v[54:55], v[6:7]
	v_mov_b64_e32 v[52:53], v[4:5]
	v_mov_b64_e32 v[50:51], v[2:3]
	v_mov_b64_e32 v[48:49], v[0:1]
	v_mov_b64_e32 v[76:77], v[12:13]
	v_mov_b64_e32 v[74:75], v[10:11]
	v_mov_b64_e32 v[72:73], v[8:9]
	v_mov_b64_e32 v[70:71], v[6:7]
	v_mov_b64_e32 v[68:69], v[4:5]
	v_mov_b64_e32 v[66:67], v[2:3]
	v_mov_b64_e32 v[64:65], v[0:1]
	s_branch .LBB0_183

.LBB0_183:
	s_waitcnt vmcnt(20)
	s_cmp_lg_u32 s92, s56
	v_mfma_f32_32x32x16_bf16 v[80:95], v[96:99], v[236:239], 0
	v_mfma_f32_32x32x16_bf16 v[80:95], v[112:115], v[240:243], v[80:95]
	v_mfma_f32_32x32x16_bf16 v[80:95], v[116:119], v[244:247], v[80:95]
	v_mfma_f32_32x32x16_bf16 v[80:95], v[120:123], v[248:251], v[80:95]
	s_cbranch_scc1 .LBB0_185
	s_nop 10
	v_cndmask_b32_e64 v0, v80, v226, s[8:9]
	v_cndmask_b32_e64 v81, v226, v81, s[10:11]
	v_cndmask_b32_e64 v80, v0, v80, s[10:11]
	v_cndmask_b32_e64 v82, v82, v226, s[12:13]
	v_cndmask_b32_e64 v83, v83, v226, s[14:15]
	v_cndmask_b32_e64 v84, v84, v226, s[16:17]
	v_cndmask_b32_e64 v85, v85, v226, s[18:19]
	v_cndmask_b32_e64 v86, v86, v226, s[20:21]
	v_cndmask_b32_e64 v87, v87, v226, s[22:23]
	v_cndmask_b32_e64 v88, v88, v226, s[24:25]
	v_cndmask_b32_e64 v89, v89, v226, s[26:27]
	v_cndmask_b32_e64 v90, v90, v226, s[28:29]
	v_cndmask_b32_e64 v91, v91, v226, s[30:31]
	v_cndmask_b32_e64 v92, v92, v226, s[34:35]
	v_cndmask_b32_e64 v93, v93, v226, s[36:37]
	v_cndmask_b32_e64 v94, v94, v226, s[38:39]
	v_cndmask_b32_e64 v95, v95, v226, s[40:41]

.LBB0_187:
	s_add_i32 s2, s56, 2
	s_min_u32 s2, s2, s92
	s_lshl_b32 s60, s2, 12
	v_lshl_add_u64 v[2:3], v[206:207], 0, s[60:61]
	global_load_dwordx4 v[96:99], v[2:3], off offset:0
	global_load_dwordx4 v[112:115], v[2:3], off offset:0x400
	global_load_dwordx4 v[116:119], v[2:3], off offset:0x800
	global_load_dwordx4 v[120:123], v[2:3], off offset:0xc00
	v_sub_f32_e32 v0, v80, v210
	v_sub_f32_e32 v2, v81, v210
	v_sub_f32_e32 v3, v82, v210
	v_sub_f32_e32 v4, v83, v210
	v_sub_f32_e32 v5, v84, v210
	v_sub_f32_e32 v6, v85, v210
	v_sub_f32_e32 v7, v86, v210
	v_sub_f32_e32 v8, v87, v210
	v_exp_f32_e32 v0, v0
	v_exp_f32_e32 v2, v2
	v_exp_f32_e32 v3, v3
	v_exp_f32_e32 v4, v4
	v_exp_f32_e32 v5, v5
	v_exp_f32_e32 v6, v6
	v_exp_f32_e32 v7, v7
	v_exp_f32_e32 v9, v8
	v_sub_f32_e32 v80, v95, v210
	v_exp_f32_e32 v212, v80
	v_cvt_pk_bf16_f32 v80, v0, v2
	v_cvt_pk_bf16_f32 v81, v3, v4
	v_cvt_pk_bf16_f32 v82, v5, v6
	v_cvt_pk_bf16_f32 v83, v7, v9
	s_waitcnt vmcnt(16)
	v_sub_f32_e32 v12, v91, v210
	v_sub_f32_e32 v8, v88, v210
	v_mfma_f32_32x32x16_bf16 v[64:79], v[100:103], v[80:83], v[64:79]
	v_sub_f32_e32 v10, v89, v210
	v_sub_f32_e32 v11, v90, v210
	v_exp_f32_e32 v13, v12
	v_sub_f32_e32 v12, v92, v210
	v_sub_f32_e32 v14, v93, v210
	v_sub_f32_e32 v15, v94, v210
	v_exp_f32_e32 v8, v8
	v_mfma_f32_32x32x16_bf16 v[48:63], v[128:131], v[80:83], v[48:63]
	v_exp_f32_e32 v10, v10
	v_exp_f32_e32 v11, v11
	v_exp_f32_e32 v12, v12
	v_exp_f32_e32 v14, v14
	v_exp_f32_e32 v15, v15
	v_cvt_pk_bf16_f32 v84, v8, v10
	v_cvt_pk_bf16_f32 v85, v11, v13
	v_mfma_f32_32x32x16_bf16 v[32:47], v[136:139], v[80:83], v[32:47]
	v_cvt_pk_bf16_f32 v86, v12, v14
	v_cvt_pk_bf16_f32 v87, v15, v212
	s_lshl_b32 s60, s2, 13
	v_mov_b32_e32 v213, v205
	s_add_i32 s2, s56, 1
	s_cmp_lg_u32 s2, s92
	v_mfma_f32_32x32x16_bf16 v[16:31], v[144:147], v[80:83], v[16:31]
	v_lshl_add_u64 v[80:81], v[208:209], 0, s[60:61]
	v_lshl_add_u64 v[82:83], v[80:81], 0, s[78:79]
	v_mfma_f32_32x32x16_bf16 v[64:79], v[124:127], v[84:87], v[64:79]
	v_mfma_f32_32x32x16_bf16 v[48:63], v[132:135], v[84:87], v[48:63]
	v_mfma_f32_32x32x16_bf16 v[32:47], v[140:143], v[84:87], v[32:47]
	v_mfma_f32_32x32x16_bf16 v[16:31], v[148:151], v[84:87], v[16:31]
	global_load_dwordx4 v[100:103], v[80:81], off offset:0
	global_load_dwordx4 v[124:127], v[80:81], off offset:0x400
	global_load_dwordx4 v[128:131], v[80:81], off offset:0x800
	global_load_dwordx4 v[132:135], v[80:81], off offset:0xc00
	global_load_dwordx4 v[136:139], v[82:83], off offset:0
	global_load_dwordx4 v[140:143], v[82:83], off offset:0x400
	global_load_dwordx4 v[144:147], v[82:83], off offset:0x800
	global_load_dwordx4 v[148:151], v[82:83], off offset:0xc00
	s_waitcnt vmcnt(20)
	v_mfma_f32_32x32x16_bf16 v[80:95], v[152:155], v[236:239], 0
	v_mfma_f32_32x32x16_bf16 v[80:95], v[156:159], v[240:243], v[80:95]
	v_mfma_f32_32x32x16_bf16 v[80:95], v[160:163], v[244:247], v[80:95]
	v_mfma_f32_32x32x16_bf16 v[80:95], v[164:167], v[248:251], v[80:95]
	s_cbranch_scc1 .LBB0_189
	s_nop 10
	v_cndmask_b32_e64 v213, v80, v226, s[8:9]
	v_cndmask_b32_e64 v81, v226, v81, s[10:11]
	v_cndmask_b32_e64 v80, v213, v80, s[10:11]
	v_cndmask_b32_e64 v82, v82, v226, s[12:13]
	v_cndmask_b32_e64 v83, v83, v226, s[14:15]
	v_cndmask_b32_e64 v84, v84, v226, s[16:17]
	v_cndmask_b32_e64 v85, v85, v226, s[18:19]
	v_cndmask_b32_e64 v86, v86, v226, s[20:21]
	v_cndmask_b32_e64 v87, v87, v226, s[22:23]
	v_cndmask_b32_e64 v88, v88, v226, s[24:25]
	v_cndmask_b32_e64 v89, v89, v226, s[26:27]
	v_cndmask_b32_e64 v90, v90, v226, s[28:29]
	v_cndmask_b32_e64 v91, v91, v226, s[30:31]
	v_cndmask_b32_e64 v92, v92, v226, s[34:35]
	v_cndmask_b32_e64 v93, v93, v226, s[36:37]
	v_cndmask_b32_e64 v94, v94, v226, s[38:39]
	v_cndmask_b32_e64 v95, v95, v226, s[40:41]
